# peeled first GEMM k-iteration (no accumulator zero-fill) and xcd barrier instead of cg grid sync after step 0, on top of attention static priority
# speedup vs baseline: 1.0476x; 1.0058x over previous
; __device__ __forceinline__ size_t a_base(const GDesc& d, const Unit& u, size_t tstepA) { return (size_t)u.pm * tstepA + (d.amode == 1 ? (size_t)u.pn * 512 : (size_t)0); }
; #define PG8_STAGE(bufoff, gbase, voff) do { _Pragma("unroll") for (int _i = 0; _i < 2; ++_i) \
;         __builtin_amdgcn_global_load_lds((const unsigned*)((const char*)(gbase) + (voff)[_i]), (LAS unsigned*)(lds + (bufoff) + ldsw + _i * 8192), 16, 0, 0); } while (0)
; __device__ __forceinline__ void gemm_generic(LAS unsigned char* lds, const GDesc& d, int G, int bx) {
;     ...
;     Unit cur, nxt; int ui = 0;
;     if (!S.next(0, cur)) return;
;     f32x4 acc[2][2][4][2];
; #pragma unroll
;     for (int a = 0; a < 2; ++a)
; #pragma unroll
;         for (int b = 0; b < 2; ++b)
; #pragma unroll
;             for (int m = 0; m < 4; ++m)
; #pragma unroll
;                 for (int n = 0; n < 2; ++n) acc[a][b][m][n] = (f32x4){0.f, 0.f, 0.f, 0.f};
;     bf16x8 At[4][2], B0[2][2], B1[2][2];
;     const char* cA = d.A + a_base(d, cur, tstepA); const char* cB = d.Bt + (size_t)cur.pn * tstepB;
;     {
;         const char* cA1 = cA + a_koff(d, 1);
;         PG8_STAGE(PG8_SB(0, 0), cB, voffB); PG8_STAGE(PG8_SB(0, 1), cB + hstepB, voffB); PG8_STAGE(PG8_SA(0, 0), cA, voffA); PG8_STAGE(PG8_SA(0, 1), cA + hstepA, voffA);
.LBB0_251:
	s_add_u32 s12, s8, s74
	s_addc_u32 s13, s9, s75
	s_add_u32 s0, s2, 0x80
	s_addc_u32 s1, s3, 0
	s_add_u32 s15, s24, 0x100
	s_addc_u32 s16, s25, 0
	s_mov_b32 s17, 0
	s_mov_b64 s[10:11], 0x200
	s_waitcnt lgkmcnt(0)
	s_branch .LBB0_254

; __device__ __forceinline__ size_t a_base(const GDesc& d, const Unit& u, size_t tstepA) { return (size_t)u.pm * tstepA + (d.amode == 1 ? (size_t)u.pn * 512 : (size_t)0); }
; #define PG8_STAGE(bufoff, gbase, voff) do { _Pragma("unroll") for (int _i = 0; _i < 2; ++_i) \
;         __builtin_amdgcn_global_load_lds((const unsigned*)((const char*)(gbase) + (voff)[_i]), (LAS unsigned*)(lds + (bufoff) + ldsw + _i * 8192), 16, 0, 0); } while (0)
; #define PG8_LDA(dst, b, h) do { _Pragma("unroll") for (int m = 0; m < 4; ++m) _Pragma("unroll") for (int k = 0; k < 2; ++k) dst[m][k] = *(const LAS bf16x8*)(lds + PG8_SA(b, h) + aoff + m * 2048 + k * 1024); } while (0)
; #define PG8_LDB(dst, b, h) do { _Pragma("unroll") for (int n = 0; n < 2; ++n) _Pragma("unroll") for (int k = 0; k < 2; ++k) dst[n][k] = *(const LAS bf16x8*)(lds + PG8_SB(b, h) + boff + n * 2048 + k * 1024); } while (0)
; #define PG8_WAIT_V(n) asm volatile("s_waitcnt vmcnt(" #n ")" ::: "memory")
; #define PG8_WAIT_L(n) asm volatile("s_waitcnt lgkmcnt(" #n ")" ::: "memory")
; #define PG8_BAR __builtin_amdgcn_s_barrier()
; #define PG8_SCHED __builtin_amdgcn_sched_barrier(0)
; __device__ __forceinline__ void gemm_generic(LAS unsigned char* lds, const GDesc& d, int G, int bx) {
;     ...
;         const bool has_next = S.next(ui + 1, nxt);
;         const char* nA = has_next ? d.A + a_base(d, nxt, tstepA) : cA; const char* nB = has_next ? d.Bt + (size_t)nxt.pn * tstepB : cB;
;         for (int t = 0; t < nt; t += 2) {
;             const bool last = (t == nt - 2);
;             const char* a1 = cA + a_koff(d, t + 1);
;             const char* a2 = last ? nA : cA + a_koff(d, t + 2); const char* b2 = last ? nB : cB + (size_t)(t + 2) * kstep;
;             const char* a3 = last ? nA + a_koff(d, 1) : cA + a_koff(d, t + 3); const char* b3 = b2 + kstep;
;             PG8_LDB(B0, 0, 0); PG8_LDB(B1, 0, 1); PG8_SCHED; PG8_LDA(At, 0, 0); PG8_STAGE(PG8_SA(1, 1), a1 + hstepA, voffA);
;             PG8_WAIT_V(8); PG8_WAIT_L(0); PG8_BAR; PG8_MMA(0, 0, At, B0); PG8_MMA(0, 1, At, B1); PG8_BAR; PG8_SCHED;
;             PG8_LDA(At, 0, 1); PG8_STAGE(PG8_SB(0, 0), b2, voffB); PG8_STAGE(PG8_SB(0, 1), b2 + hstepB, voffB); PG8_STAGE(PG8_SA(0, 0), a2, voffA);
;             PG8_WAIT_V(8); PG8_WAIT_L(0); PG8_BAR; PG8_MMA(1, 0, At, B0); PG8_MMA(1, 1, At, B1); PG8_BAR; PG8_SCHED;
.LBB0_253:
	s_and_b64 s[44:45], exec, s[44:45]
	s_cselect_b32 s45, s83, s16
	s_cselect_b32 s44, s82, s15
	ds_read_b128 v[130:133], v250
	ds_read_b128 v[134:137], v250 offset:1024
	ds_read_b128 v[138:141], v250 offset:2048
	ds_read_b128 v[142:145], v250 offset:3072
	ds_read_b128 v[146:149], v251
	ds_read_b128 v[150:153], v251 offset:1024
	ds_read_b128 v[154:157], v251 offset:2048
	ds_read_b128 v[158:161], v251 offset:3072
	s_add_u32 s34, s12, s34
	s_addc_u32 s35, s13, s35
	s_add_i32 m0, s97, 0xc000
	ds_read_b128 v[162:165], v232
	ds_read_b128 v[166:169], v232 offset:1024
	ds_read_b128 v[170:173], v232 offset:2048
	ds_read_b128 v[174:177], v232 offset:3072
	ds_read_b128 v[178:181], v232 offset:4096
	ds_read_b128 v[182:185], v232 offset:5120
	ds_read_b128 v[186:189], v232 offset:6144
	ds_read_b128 v[190:193], v232 offset:7168
	global_load_lds_dwordx4 v198, s[34:35]
	s_add_i32 m0, s97, 0xe000
	s_nop 0
	global_load_lds_dwordx4 v202, s[34:35]
	s_waitcnt vmcnt(8)
	s_waitcnt lgkmcnt(0)
	s_barrier
	s_setprio 1
	s_waitcnt lgkmcnt(0)
	v_mfma_f32_16x16x32_bf16 v[124:127], v[130:133], v[162:165], 0
	v_mfma_f32_16x16x32_bf16 v[120:123], v[138:141], v[162:165], 0
	v_mfma_f32_16x16x32_bf16 v[112:115], v[130:133], v[170:173], 0
	v_mfma_f32_16x16x32_bf16 v[104:107], v[138:141], v[170:173], 0
	v_mfma_f32_16x16x32_bf16 v[96:99], v[130:133], v[178:181], 0
	v_mfma_f32_16x16x32_bf16 v[88:91], v[138:141], v[178:181], 0
	v_mfma_f32_16x16x32_bf16 v[80:83], v[130:133], v[186:189], 0
	v_mfma_f32_16x16x32_bf16 v[72:75], v[138:141], v[186:189], 0
	v_mfma_f32_16x16x32_bf16 v[124:127], v[134:137], v[166:169], v[124:127]
	v_mfma_f32_16x16x32_bf16 v[120:123], v[142:145], v[166:169], v[120:123]
	v_mfma_f32_16x16x32_bf16 v[112:115], v[134:137], v[174:177], v[112:115]
	v_mfma_f32_16x16x32_bf16 v[104:107], v[142:145], v[174:177], v[104:107]
	v_mfma_f32_16x16x32_bf16 v[96:99], v[134:137], v[182:185], v[96:99]
	v_mfma_f32_16x16x32_bf16 v[88:91], v[142:145], v[182:185], v[88:91]
	v_mfma_f32_16x16x32_bf16 v[80:83], v[134:137], v[190:193], v[80:83]
	v_mfma_f32_16x16x32_bf16 v[72:75], v[142:145], v[190:193], v[72:75]
	s_setprio 0
	s_setprio 1
	v_mfma_f32_16x16x32_bf16 v[116:119], v[146:149], v[162:165], 0
	v_mfma_f32_16x16x32_bf16 v[108:111], v[154:157], v[162:165], 0
	v_mfma_f32_16x16x32_bf16 v[100:103], v[146:149], v[170:173], 0
	v_mfma_f32_16x16x32_bf16 v[92:95], v[154:157], v[170:173], 0
	v_mfma_f32_16x16x32_bf16 v[84:87], v[146:149], v[178:181], 0
	v_mfma_f32_16x16x32_bf16 v[76:79], v[154:157], v[178:181], 0
	v_mfma_f32_16x16x32_bf16 v[68:71], v[146:149], v[186:189], 0
	v_mfma_f32_16x16x32_bf16 v[64:67], v[154:157], v[186:189], 0
	v_mfma_f32_16x16x32_bf16 v[116:119], v[150:153], v[166:169], v[116:119]
	v_mfma_f32_16x16x32_bf16 v[108:111], v[158:161], v[166:169], v[108:111]
	v_mfma_f32_16x16x32_bf16 v[100:103], v[150:153], v[174:177], v[100:103]
	v_mfma_f32_16x16x32_bf16 v[92:95], v[158:161], v[174:177], v[92:95]
	v_mfma_f32_16x16x32_bf16 v[84:87], v[150:153], v[182:185], v[84:87]
	v_mfma_f32_16x16x32_bf16 v[76:79], v[158:161], v[182:185], v[76:79]
	v_mfma_f32_16x16x32_bf16 v[68:71], v[150:153], v[190:193], v[68:71]
	v_mfma_f32_16x16x32_bf16 v[64:67], v[158:161], v[190:193], v[64:67]
	s_setprio 0
	s_barrier
	s_add_i32 m0, s95, 0x10000
	ds_read_b128 v[162:165], v232 offset:16384
	ds_read_b128 v[166:169], v232 offset:17408
	ds_read_b128 v[170:173], v232 offset:18432
	ds_read_b128 v[174:177], v232 offset:19456
	ds_read_b128 v[178:181], v232 offset:20480
	ds_read_b128 v[182:185], v232 offset:21504
	ds_read_b128 v[186:189], v232 offset:22528
	ds_read_b128 v[190:193], v232 offset:23552
	global_load_lds_dwordx4 v200, s[44:45]
	s_add_i32 m0, s95, 0x12000
	s_add_u32 s34, s44, s76
	s_addc_u32 s35, s45, s77
	global_load_lds_dwordx4 v204, s[44:45]
	s_add_i32 m0, s95, 0x14000
	s_nop 0
	global_load_lds_dwordx4 v200, s[34:35]
	s_add_i32 m0, s95, 0x16000
	s_nop 0
	global_load_lds_dwordx4 v204, s[34:35]
	s_mov_b32 m0, s97
	s_nop 0
	global_load_lds_dwordx4 v198, s[28:29]
	s_mov_b32 m0, s27
	s_nop 0
	global_load_lds_dwordx4 v202, s[28:29]
	s_waitcnt vmcnt(8)
	s_waitcnt lgkmcnt(0)
	s_barrier
	s_setprio 1
	s_waitcnt lgkmcnt(0)
	v_mfma_f32_16x16x32_bf16 v[60:63], v[130:133], v[162:165], 0
	v_mfma_f32_16x16x32_bf16 v[56:59], v[138:141], v[162:165], 0
	v_mfma_f32_16x16x32_bf16 v[48:51], v[130:133], v[170:173], 0
	v_mfma_f32_16x16x32_bf16 v[40:43], v[138:141], v[170:173], 0
	v_mfma_f32_16x16x32_bf16 v[32:35], v[130:133], v[178:181], 0
	v_mfma_f32_16x16x32_bf16 v[24:27], v[138:141], v[178:181], 0
	v_mfma_f32_16x16x32_bf16 v[16:19], v[130:133], v[186:189], 0
	v_mfma_f32_16x16x32_bf16 v[8:11], v[138:141], v[186:189], 0
	v_mfma_f32_16x16x32_bf16 v[60:63], v[134:137], v[166:169], v[60:63]
	v_mfma_f32_16x16x32_bf16 v[56:59], v[142:145], v[166:169], v[56:59]
	v_mfma_f32_16x16x32_bf16 v[48:51], v[134:137], v[174:177], v[48:51]
	v_mfma_f32_16x16x32_bf16 v[40:43], v[142:145], v[174:177], v[40:43]
	v_mfma_f32_16x16x32_bf16 v[32:35], v[134:137], v[182:185], v[32:35]
	v_mfma_f32_16x16x32_bf16 v[24:27], v[142:145], v[182:185], v[24:27]
	v_mfma_f32_16x16x32_bf16 v[16:19], v[134:137], v[190:193], v[16:19]
	v_mfma_f32_16x16x32_bf16 v[8:11], v[142:145], v[190:193], v[8:11]
	s_setprio 0
	s_setprio 1
	v_mfma_f32_16x16x32_bf16 v[52:55], v[146:149], v[162:165], 0
	v_mfma_f32_16x16x32_bf16 v[44:47], v[154:157], v[162:165], 0
	v_mfma_f32_16x16x32_bf16 v[36:39], v[146:149], v[170:173], 0
	v_mfma_f32_16x16x32_bf16 v[28:31], v[154:157], v[170:173], 0
	v_mfma_f32_16x16x32_bf16 v[20:23], v[146:149], v[178:181], 0
	v_mfma_f32_16x16x32_bf16 v[12:15], v[154:157], v[178:181], 0
	v_mfma_f32_16x16x32_bf16 v[4:7], v[146:149], v[186:189], 0
	v_mfma_f32_16x16x32_bf16 v[0:3], v[154:157], v[186:189], 0
	v_mfma_f32_16x16x32_bf16 v[52:55], v[150:153], v[166:169], v[52:55]
	v_mfma_f32_16x16x32_bf16 v[44:47], v[158:161], v[166:169], v[44:47]
	v_mfma_f32_16x16x32_bf16 v[36:39], v[150:153], v[174:177], v[36:39]
	v_mfma_f32_16x16x32_bf16 v[28:31], v[158:161], v[174:177], v[28:31]
	v_mfma_f32_16x16x32_bf16 v[20:23], v[150:153], v[182:185], v[20:23]
	v_mfma_f32_16x16x32_bf16 v[12:15], v[158:161], v[182:185], v[12:15]
	v_mfma_f32_16x16x32_bf16 v[4:7], v[150:153], v[190:193], v[4:7]
	v_mfma_f32_16x16x32_bf16 v[0:3], v[158:161], v[190:193], v[0:3]
	s_setprio 0
	s_barrier
; #define PG8_STAGE(bufoff, gbase, voff) do { _Pragma("unroll") for (int _i = 0; _i < 2; ++_i) \
;         __builtin_amdgcn_global_load_lds((const unsigned*)((const char*)(gbase) + (voff)[_i]), (LAS unsigned*)(lds + (bufoff) + ldsw + _i * 8192), 16, 0, 0); } while (0)
; #define PG8_LDA(dst, b, h) do { _Pragma("unroll") for (int m = 0; m < 4; ++m) _Pragma("unroll") for (int k = 0; k < 2; ++k) dst[m][k] = *(const LAS bf16x8*)(lds + PG8_SA(b, h) + aoff + m * 2048 + k * 1024); } while (0)
; #define PG8_LDB(dst, b, h) do { _Pragma("unroll") for (int n = 0; n < 2; ++n) _Pragma("unroll") for (int k = 0; k < 2; ++k) dst[n][k] = *(const LAS bf16x8*)(lds + PG8_SB(b, h) + boff + n * 2048 + k * 1024); } while (0)
; #define PG8_MMA(ai, bj, At, Bt) do { __builtin_amdgcn_s_setprio(1); _Pragma("unroll") for (int m = 0; m < 4; ++m) _Pragma("unroll") for (int n = 0; n < 2; ++n) _Pragma("unroll") for (int k = 0; k < 2; ++k) \
;         acc[ai][bj][m][n] = __builtin_amdgcn_mfma_f32_16x16x32_bf16(Bt[n][k], At[m][k], acc[ai][bj][m][n], 0, 0, 0); __builtin_amdgcn_s_setprio(0); } while (0)
; #define PG8_WAIT_V(n) asm volatile("s_waitcnt vmcnt(" #n ")" ::: "memory")
; #define PG8_WAIT_L(n) asm volatile("s_waitcnt lgkmcnt(" #n ")" ::: "memory")
; #define PG8_BAR __builtin_amdgcn_s_barrier()
; #define PG8_SCHED __builtin_amdgcn_sched_barrier(0)
; __device__ __forceinline__ void gemm_generic(LAS unsigned char* lds, const GDesc& d, int G, int bx) {
;     ...
;         for (int t = 0; t < nt; t += 2) {
;             const bool last = (t == nt - 2);
;             const char* a1 = cA + a_koff(d, t + 1);
;             const char* a2 = last ? nA : cA + a_koff(d, t + 2); const char* b2 = last ? nB : cB + (size_t)(t + 2) * kstep;
;             const char* a3 = last ? nA + a_koff(d, 1) : cA + a_koff(d, t + 3); const char* b3 = b2 + kstep;
;     ...
;             PG8_LDB(B0, 1, 0); PG8_LDB(B1, 1, 1); PG8_SCHED; PG8_LDA(At, 1, 0); PG8_STAGE(PG8_SA(0, 1), a2 + hstepA, voffA);
;             PG8_WAIT_V(8); PG8_WAIT_L(0); PG8_BAR; PG8_MMA(0, 0, At, B0); PG8_MMA(0, 1, At, B1); PG8_BAR; PG8_SCHED;
;             PG8_LDA(At, 1, 1); PG8_STAGE(PG8_SB(1, 0), b3, voffB); PG8_STAGE(PG8_SB(1, 1), b3 + hstepB, voffB); PG8_STAGE(PG8_SA(1, 0), a3, voffA);
;             PG8_WAIT_V(8); PG8_WAIT_L(0); PG8_BAR; PG8_MMA(1, 0, At, B0); PG8_MMA(1, 1, At, B1); PG8_BAR; PG8_SCHED;
	s_add_i32 s26, 0, 0x1c000
	ds_read_b128 v[130:133], v252
	ds_read_b128 v[134:137], v252 offset:1024
	ds_read_b128 v[138:141], v252 offset:2048
	ds_read_b128 v[142:145], v252 offset:3072
	ds_read_b128 v[146:149], v253
	ds_read_b128 v[150:153], v253 offset:1024
	ds_read_b128 v[154:157], v253 offset:2048
	ds_read_b128 v[158:161], v253 offset:3072
	s_add_u32 s28, s28, s74
	s_addc_u32 s29, s29, s75
	s_mov_b32 m0, s64
	ds_read_b128 v[162:165], v232 offset:32768
	ds_read_b128 v[166:169], v232 offset:33792
	ds_read_b128 v[170:173], v232 offset:34816
	ds_read_b128 v[174:177], v232 offset:35840
	ds_read_b128 v[178:181], v232 offset:36864
	ds_read_b128 v[182:185], v232 offset:37888
	ds_read_b128 v[186:189], v232 offset:38912
	ds_read_b128 v[190:193], v232 offset:39936
	global_load_lds_dwordx4 v198, s[28:29]
	s_mov_b32 m0, s65
	s_nop 0
	global_load_lds_dwordx4 v202, s[28:29]
	s_waitcnt vmcnt(8)
	s_waitcnt lgkmcnt(0)
	s_barrier
	s_setprio 1
	s_waitcnt lgkmcnt(0)
	v_mfma_f32_16x16x32_bf16 v[124:127], v[130:133], v[162:165], v[124:127]
	v_mfma_f32_16x16x32_bf16 v[120:123], v[138:141], v[162:165], v[120:123]
	v_mfma_f32_16x16x32_bf16 v[112:115], v[130:133], v[170:173], v[112:115]
	v_mfma_f32_16x16x32_bf16 v[104:107], v[138:141], v[170:173], v[104:107]
	v_mfma_f32_16x16x32_bf16 v[96:99], v[130:133], v[178:181], v[96:99]
	v_mfma_f32_16x16x32_bf16 v[88:91], v[138:141], v[178:181], v[88:91]
	v_mfma_f32_16x16x32_bf16 v[80:83], v[130:133], v[186:189], v[80:83]
	v_mfma_f32_16x16x32_bf16 v[72:75], v[138:141], v[186:189], v[72:75]
	v_mfma_f32_16x16x32_bf16 v[124:127], v[134:137], v[166:169], v[124:127]
	v_mfma_f32_16x16x32_bf16 v[120:123], v[142:145], v[166:169], v[120:123]
	v_mfma_f32_16x16x32_bf16 v[112:115], v[134:137], v[174:177], v[112:115]
	v_mfma_f32_16x16x32_bf16 v[104:107], v[142:145], v[174:177], v[104:107]
	v_mfma_f32_16x16x32_bf16 v[96:99], v[134:137], v[182:185], v[96:99]
	v_mfma_f32_16x16x32_bf16 v[88:91], v[142:145], v[182:185], v[88:91]
	v_mfma_f32_16x16x32_bf16 v[80:83], v[134:137], v[190:193], v[80:83]
	v_mfma_f32_16x16x32_bf16 v[72:75], v[142:145], v[190:193], v[72:75]
	s_setprio 0
	s_setprio 1
	v_mfma_f32_16x16x32_bf16 v[116:119], v[146:149], v[162:165], v[116:119]
	v_mfma_f32_16x16x32_bf16 v[108:111], v[154:157], v[162:165], v[108:111]
	v_mfma_f32_16x16x32_bf16 v[100:103], v[146:149], v[170:173], v[100:103]
	v_mfma_f32_16x16x32_bf16 v[92:95], v[154:157], v[170:173], v[92:95]
	v_mfma_f32_16x16x32_bf16 v[84:87], v[146:149], v[178:181], v[84:87]
	v_mfma_f32_16x16x32_bf16 v[76:79], v[154:157], v[178:181], v[76:79]
	v_mfma_f32_16x16x32_bf16 v[68:71], v[146:149], v[186:189], v[68:71]
	v_mfma_f32_16x16x32_bf16 v[64:67], v[154:157], v[186:189], v[64:67]
	v_mfma_f32_16x16x32_bf16 v[116:119], v[150:153], v[166:169], v[116:119]
	v_mfma_f32_16x16x32_bf16 v[108:111], v[158:161], v[166:169], v[108:111]
	v_mfma_f32_16x16x32_bf16 v[100:103], v[150:153], v[174:177], v[100:103]
	v_mfma_f32_16x16x32_bf16 v[92:95], v[158:161], v[174:177], v[92:95]
	v_mfma_f32_16x16x32_bf16 v[84:87], v[150:153], v[182:185], v[84:87]
	v_mfma_f32_16x16x32_bf16 v[76:79], v[158:161], v[182:185], v[76:79]
	v_mfma_f32_16x16x32_bf16 v[68:71], v[150:153], v[190:193], v[68:71]
	v_mfma_f32_16x16x32_bf16 v[64:67], v[158:161], v[190:193], v[64:67]
	s_setprio 0
	s_barrier
	s_add_u32 s46, s44, s20
	s_addc_u32 s47, s45, s21
	s_add_i32 m0, s95, 0x18000
	ds_read_b128 v[162:165], v232 offset:49152
	ds_read_b128 v[166:169], v232 offset:50176
	ds_read_b128 v[170:173], v232 offset:51200
	ds_read_b128 v[174:177], v232 offset:52224
	ds_read_b128 v[178:181], v232 offset:53248
	ds_read_b128 v[182:185], v232 offset:54272
	ds_read_b128 v[186:189], v232 offset:55296
	ds_read_b128 v[190:193], v232 offset:56320
	global_load_lds_dwordx4 v200, s[46:47]
	s_add_i32 m0, s95, 0x1a000
	s_nop 0
	global_load_lds_dwordx4 v204, s[46:47]
	s_add_u32 s46, s34, s20
	s_addc_u32 s47, s35, s21
	s_add_i32 m0, s95, 0x1c000
	s_nop 0
	global_load_lds_dwordx4 v200, s[46:47]
	s_add_i32 m0, s95, 0x1e000
	s_nop 0
	global_load_lds_dwordx4 v204, s[46:47]
	s_mov_b32 m0, s30
	s_nop 0
	global_load_lds_dwordx4 v198, s[24:25]
	s_mov_b32 m0, s31
	s_nop 0
	global_load_lds_dwordx4 v202, s[24:25]
	s_add_u32 s10, s10, 0x180
	s_addc_u32 s11, s11, 0
	s_add_u32 s15, s15, 0x100
	s_addc_u32 s16, s16, 0
	s_mov_b32 s17, s22
	s_cmp_ge_u32 s22, s87
	s_cbranch_scc1 .Lg_ctl_done_p
	s_or_b32 s22, s17, 1
	s_lshl_b64 s[34:35], s[22:23], 7
	s_add_i32 s22, s17, 2
	s_lshl_b64 s[28:29], s[22:23], 7
	s_add_i32 s24, s17, 3
	s_mov_b32 s25, s23
	s_lshl_b64 s[24:25], s[24:25], 7
	s_and_b64 vcc, exec, s[84:85]
	s_cbranch_scc1 .Lg_ctl_std_p
	s_add_u32 s34, s10, 0xfffffe80
	s_addc_u32 s35, s11, -1
	s_add_u32 s28, s10, 0xffffff80
	s_addc_u32 s29, s11, -1
	s_mov_b64 s[24:25], s[10:11]

; #define PG8_MMA(ai, bj, At, Bt) do { __builtin_amdgcn_s_setprio(1); _Pragma("unroll") for (int m = 0; m < 4; ++m) _Pragma("unroll") for (int n = 0; n < 2; ++n) _Pragma("unroll") for (int k = 0; k < 2; ++k) \
;         acc[ai][bj][m][n] = __builtin_amdgcn_mfma_f32_16x16x32_bf16(Bt[n][k], At[m][k], acc[ai][bj][m][n], 0, 0, 0); __builtin_amdgcn_s_setprio(0); } while (0)
; #define PG8_WAIT_V(n) asm volatile("s_waitcnt vmcnt(" #n ")" ::: "memory")
; #define PG8_WAIT_L(n) asm volatile("s_waitcnt lgkmcnt(" #n ")" ::: "memory")
; #define PG8_BAR __builtin_amdgcn_s_barrier()
; #define PG8_SCHED __builtin_amdgcn_sched_barrier(0)
; __device__ __forceinline__ void gemm_generic(LAS unsigned char* lds, const GDesc& d, int G, int bx) {
;     ...
;             PG8_WAIT_V(8); PG8_WAIT_L(0); PG8_BAR; PG8_MMA(1, 0, At, B0); PG8_MMA(1, 1, At, B1); PG8_BAR; PG8_SCHED;
;         }
;         if (wr == 0) PG8_BAR;
;         run_epi(d, acc, cur, wr, wc, fr, fq);
;         if (!has_next) break;
.Lg_ctl_done_p:
	s_waitcnt vmcnt(8)
	s_waitcnt lgkmcnt(0)
	s_barrier
	s_setprio 1
	s_waitcnt lgkmcnt(0)
	v_mfma_f32_16x16x32_bf16 v[60:63], v[130:133], v[162:165], v[60:63]
	v_mfma_f32_16x16x32_bf16 v[56:59], v[138:141], v[162:165], v[56:59]
	v_mfma_f32_16x16x32_bf16 v[48:51], v[130:133], v[170:173], v[48:51]
	v_mfma_f32_16x16x32_bf16 v[40:43], v[138:141], v[170:173], v[40:43]
	v_mfma_f32_16x16x32_bf16 v[32:35], v[130:133], v[178:181], v[32:35]
	v_mfma_f32_16x16x32_bf16 v[24:27], v[138:141], v[178:181], v[24:27]
	v_mfma_f32_16x16x32_bf16 v[16:19], v[130:133], v[186:189], v[16:19]
	v_mfma_f32_16x16x32_bf16 v[8:11], v[138:141], v[186:189], v[8:11]
	v_mfma_f32_16x16x32_bf16 v[60:63], v[134:137], v[166:169], v[60:63]
	v_mfma_f32_16x16x32_bf16 v[56:59], v[142:145], v[166:169], v[56:59]
	v_mfma_f32_16x16x32_bf16 v[48:51], v[134:137], v[174:177], v[48:51]
	v_mfma_f32_16x16x32_bf16 v[40:43], v[142:145], v[174:177], v[40:43]
	v_mfma_f32_16x16x32_bf16 v[32:35], v[134:137], v[182:185], v[32:35]
	v_mfma_f32_16x16x32_bf16 v[24:27], v[142:145], v[182:185], v[24:27]
	v_mfma_f32_16x16x32_bf16 v[16:19], v[134:137], v[190:193], v[16:19]
	v_mfma_f32_16x16x32_bf16 v[8:11], v[142:145], v[190:193], v[8:11]
	s_setprio 0
	s_setprio 1
	v_mfma_f32_16x16x32_bf16 v[52:55], v[146:149], v[162:165], v[52:55]
	v_mfma_f32_16x16x32_bf16 v[44:47], v[154:157], v[162:165], v[44:47]
	v_mfma_f32_16x16x32_bf16 v[36:39], v[146:149], v[170:173], v[36:39]
	v_mfma_f32_16x16x32_bf16 v[28:31], v[154:157], v[170:173], v[28:31]
	v_mfma_f32_16x16x32_bf16 v[20:23], v[146:149], v[178:181], v[20:23]
	v_mfma_f32_16x16x32_bf16 v[12:15], v[154:157], v[178:181], v[12:15]
	v_mfma_f32_16x16x32_bf16 v[4:7], v[146:149], v[186:189], v[4:7]
	v_mfma_f32_16x16x32_bf16 v[0:3], v[154:157], v[186:189], v[0:3]
	v_mfma_f32_16x16x32_bf16 v[52:55], v[150:153], v[166:169], v[52:55]
	v_mfma_f32_16x16x32_bf16 v[44:47], v[158:161], v[166:169], v[44:47]
	v_mfma_f32_16x16x32_bf16 v[36:39], v[150:153], v[174:177], v[36:39]
	v_mfma_f32_16x16x32_bf16 v[28:31], v[158:161], v[174:177], v[28:31]
	v_mfma_f32_16x16x32_bf16 v[20:23], v[150:153], v[182:185], v[20:23]
	v_mfma_f32_16x16x32_bf16 v[12:15], v[158:161], v[182:185], v[12:15]
	v_mfma_f32_16x16x32_bf16 v[4:7], v[150:153], v[190:193], v[4:7]
	v_mfma_f32_16x16x32_bf16 v[0:3], v[158:161], v[190:193], v[0:3]
	s_setprio 0
	s_barrier
	s_cmp_ge_u32 s17, s87
	s_cbranch_scc1 .LBB0_267

; __device__ __forceinline__ unsigned xb_add(unsigned* p, unsigned v) { return __hip_atomic_fetch_add(p, v, __ATOMIC_RELAXED, __HIP_MEMORY_SCOPE_AGENT); }
; __device__ __forceinline__ void xcd_barrier(const XcdBarrier& b) {
;     asm volatile("s_waitcnt vmcnt(0)" ::: "memory");
;     __syncthreads();
;     if (threadIdx.x == 0) {
;         unsigned* bar = b.bar;
;         __builtin_amdgcn_s_waitcnt(0);
;         unsigned nloc = b.st[0], nx = b.st[1];
;         if (nloc == 0u) { xcd_barrier_complete(bar, b.x, nloc, nx); b.st[0] = nloc; b.st[1] = nx; }
;         const unsigned old = xb_add(&bar[XB_XSUB(b.x)], 1u);
; __global__ void __launch_bounds__(512, 2) fwd_megakernel(Params P) {
;     ...
;         if (sync && step != 27) { if (step == 0) grid.sync(); else xcd_barrier(bar); }
.LBB0_1937:
	s_cmp_eq_u32 s17, 27
	s_cselect_b64 s[2:3], -1, 0
	s_xor_b64 s[0:1], s[0:1], -1
	s_or_b64 s[0:1], s[2:3], s[0:1]
	s_and_b64 vcc, exec, s[0:1]
	s_cbranch_vccnz .LBB0_126
	s_waitcnt vmcnt(0)
	s_waitcnt vmcnt(0) lgkmcnt(0)
	s_barrier
	s_mov_b64 s[0:1], exec
	v_readlane_b32 s2, v249, 13
	v_readlane_b32 s3, v249, 14
	s_and_b64 s[2:3], s[0:1], s[2:3]
	s_mov_b64 exec, s[2:3]
	s_cbranch_execz .LBB0_1993
	v_readlane_b32 s2, v246, 3
	s_waitcnt vmcnt(0) expcnt(0) lgkmcnt(0)
	s_nop 0
	v_mov_b32_e32 v0, s2
	ds_read_b32 v2, v0
	v_readlane_b32 s2, v246, 4
	s_waitcnt lgkmcnt(0)
	v_cmp_ne_u32_e32 vcc, 0, v2
	v_mov_b32_e32 v0, s2
	ds_read_b32 v0, v0
	s_cbranch_vccnz .LBB0_1956
	s_mov_b32 s8, 1
	s_branch .LBB0_1943
